# P3 row loop: the LSE and dilated-group loads are issued together with the attention-output loads at the top of each row iteration (one memory round trip per row instead of two)
# speedup vs baseline: 1.0004x; 1.0004x over previous
.LBB0_396:
	s_nop 0
	v_lshl_add_u64 v[6:7], v[30:31], 0, s[82:83]
	s_mov_b32 s1, 0xda00000
	v_add_co_u32_e64 v34, s[4:5], s1, v6
	v_lshl_add_u64 v[8:9], v[28:29], 0, s[82:83]
	s_nop 0
	v_addc_co_u32_e64 v35, s[4:5], 0, v7, s[4:5]
	s_mov_b32 s1, 0x20a00000
	v_add_co_u32_e64 v40, s[4:5], s1, v8
	s_mov_b32 s1, 0x20a40000
	s_nop 0
	v_addc_co_u32_e64 v41, s[4:5], 0, v9, s[4:5]
	v_add_co_u32_e64 v42, s[4:5], s1, v8
	s_mov_b32 s1, 0x20a80000
	s_nop 0
	v_addc_co_u32_e64 v43, s[4:5], 0, v9, s[4:5]
	v_add_co_u32_e64 v44, s[4:5], s1, v8
	v_lshl_add_u64 v[10:11], v[26:27], 0, s[82:83]
	s_nop 0
	v_addc_co_u32_e64 v45, s[4:5], 0, v9, s[4:5]
	s_mov_b32 s1, 0x1da00000
	v_add_co_u32_e64 v46, s[4:5], s1, v10
	s_mov_b32 s1, 0x1ea00000
	s_nop 0
	v_addc_co_u32_e64 v47, s[4:5], 0, v11, s[4:5]
	v_lshl_add_u64 v[4:5], v[32:33], 0, s[82:83]
	v_add_co_u32_e64 v48, s[4:5], s1, v10
	v_add_co_u32_e32 v14, vcc, 0x8a00000, v4
	s_nop 0
	v_addc_co_u32_e64 v49, s[4:5], 0, v11, s[4:5]
	s_mov_b32 s1, 0x1fa00000
	v_add_co_u32_e64 v50, s[4:5], s1, v10
	v_addc_co_u32_e32 v15, vcc, 0, v5, vcc
	s_nop 0
	v_addc_co_u32_e64 v51, s[4:5], 0, v11, s[4:5]
	global_load_dwordx4 v[4:7], v[14:15], off
	global_load_dwordx4 v[8:11], v[14:15], off offset:256
	global_load_dword v60, v[40:41], off
	global_load_dword v61, v[42:43], off
	global_load_dword v62, v[44:45], off
	global_load_dwordx4 v[64:67], v[46:47], off
	global_load_dwordx4 v[68:71], v[48:49], off
	global_load_dwordx4 v[72:75], v[50:51], off
	v_xor_b32_e32 v13, 0x80000000, v3
	v_xor_b32_e32 v12, 0x80000000, v2
	s_mov_b64 s[4:5], 0x100000
	v_lshl_add_u64 v[26:27], v[26:27], 0, s[4:5]
	s_mov_b64 s[4:5], 0x300000
	v_lshl_add_u64 v[30:31], v[30:31], 0, s[4:5]
	s_mov_b64 s[4:5], 0x200000
	v_lshl_add_u64 v[32:33], v[32:33], 0, s[4:5]
	s_addk_i32 s6, 0x400
	v_lshl_add_u64 v[28:29], v[28:29], 0, s[68:69]
	s_cmp_ge_i32 s6, s0
	s_waitcnt vmcnt(7)
	v_lshlrev_b32_e32 v14, 16, v4
	v_and_b32_e32 v15, 0xffff0000, v4
	v_lshlrev_b32_e32 v4, 16, v5
	v_and_b32_e32 v5, 0xffff0000, v5
	v_lshlrev_b32_e32 v52, 16, v6
	v_and_b32_e32 v53, 0xffff0000, v6
	s_waitcnt vmcnt(6)
	v_lshlrev_b32_e32 v54, 16, v8
	v_and_b32_e32 v55, 0xffff0000, v8
	v_lshlrev_b32_e32 v8, 16, v9
	v_and_b32_e32 v9, 0xffff0000, v9
	v_lshlrev_b32_e32 v56, 16, v10
	v_and_b32_e32 v57, 0xffff0000, v10
	v_lshlrev_b32_e32 v6, 16, v7
	v_and_b32_e32 v7, 0xffff0000, v7
	v_lshlrev_b32_e32 v10, 16, v11
	v_and_b32_e32 v11, 0xffff0000, v11
	v_pk_fma_f32 v[4:5], v[12:13], v[8:9], v[4:5]
	v_pk_fma_f32 v[8:9], v[24:25], v[56:57], v[52:53] neg_lo:[1,0,0] neg_hi:[1,0,0]
	v_pk_fma_f32 v[14:15], v[24:25], v[54:55], v[14:15] neg_lo:[1,0,0] neg_hi:[1,0,0]
	v_pk_fma_f32 v[6:7], v[12:13], v[10:11], v[6:7]
	v_pk_mul_f32 v[10:11], v[8:9], v[8:9]
	v_pk_mul_f32 v[12:13], v[6:7], v[6:7]
	v_pk_fma_f32 v[10:11], v[14:15], v[14:15], v[10:11]
	v_pk_fma_f32 v[12:13], v[4:5], v[4:5], v[12:13]
	v_add_f32_e32 v10, v10, v11
	v_add_f32_e32 v10, v10, v12
	v_add_f32_e32 v10, v10, v13
	ds_bpermute_b32 v11, v1, v10
	s_waitcnt lgkmcnt(0)
	v_add_f32_e32 v10, v10, v11
	ds_bpermute_b32 v11, v36, v10
	s_waitcnt lgkmcnt(0)
	v_add_f32_e32 v10, v10, v11
	ds_bpermute_b32 v11, v37, v10
	s_waitcnt lgkmcnt(0)
	v_add_f32_e32 v10, v10, v11
	ds_bpermute_b32 v11, v38, v10
	s_waitcnt lgkmcnt(0)
	v_add_f32_e32 v10, v10, v11
	v_fmamk_f32 v10, v10, 0x3c000000, v254
	v_rsq_f32_e32 v10, v10
	s_nop 0
	v_pk_mul_f32 v[12:13], v[14:15], v[10:11] op_sel_hi:[1,0]
	v_pk_mul_f32 v[4:5], v[4:5], v[10:11] op_sel_hi:[1,0]
	v_pk_mul_f32 v[8:9], v[8:9], v[10:11] op_sel_hi:[1,0]
	v_pk_mul_f32 v[6:7], v[6:7], v[10:11] op_sel_hi:[1,0]
	v_pk_mul_f32 v[10:11], v[16:17], v[4:5]
	v_pk_mul_f32 v[4:5], v[18:19], v[12:13]
	v_pk_mul_f32 v[12:13], v[20:21], v[6:7]
	v_pk_mul_f32 v[6:7], v[22:23], v[8:9]
	v_cvt_pk_bf16_f32 v4, v4, v5
	v_cvt_pk_bf16_f32 v5, v10, v11
	v_cvt_pk_bf16_f32 v6, v6, v7
	v_cvt_pk_bf16_f32 v7, v12, v13
	global_store_dwordx4 v[34:35], v[4:7], off
	s_waitcnt vmcnt(1)
	v_mov_b32_e32 v39, v60
	v_mov_b32_e32 v52, v61
	v_mov_b32_e32 v53, v62
	v_mov_b32_e32 v12, v64
	v_mov_b32_e32 v13, v65
	v_mov_b32_e32 v14, v66
	v_mov_b32_e32 v15, v67
	v_mov_b32_e32 v8, v68
	v_mov_b32_e32 v9, v69
	v_mov_b32_e32 v10, v70
	v_mov_b32_e32 v11, v71
	v_mov_b32_e32 v4, v72
	v_mov_b32_e32 v5, v73
	v_mov_b32_e32 v6, v74
	v_mov_b32_e32 v7, v75
	v_max3_f32 v54, v39, v52, v53
	v_sub_f32_e32 v39, v39, v54
	v_sub_f32_e32 v52, v52, v54
	v_sub_f32_e32 v53, v53, v54
	v_mul_f32_e32 v39, 0x3fb8aa3b, v39
	v_mul_f32_e32 v54, 0x3fb8aa3b, v52
	v_mul_f32_e32 v53, 0x3fb8aa3b, v53
	v_exp_f32_e32 v52, v39
	v_exp_f32_e32 v54, v54
	v_exp_f32_e32 v56, v53
	v_lshlrev_b32_e32 v44, 16, v8
	v_and_b32_e32 v45, 0xffff0000, v8
	v_lshlrev_b32_e32 v8, 16, v9
	v_and_b32_e32 v9, 0xffff0000, v9
	v_lshlrev_b32_e32 v46, 16, v10
	v_and_b32_e32 v47, 0xffff0000, v10
	v_lshlrev_b32_e32 v10, 16, v11
	v_and_b32_e32 v11, 0xffff0000, v11
	v_add_f32_e32 v39, v52, v54
	v_lshlrev_b32_e32 v40, 16, v12
	v_and_b32_e32 v41, 0xffff0000, v12
	v_lshlrev_b32_e32 v12, 16, v13
	v_and_b32_e32 v13, 0xffff0000, v13
	v_lshlrev_b32_e32 v42, 16, v14
	v_and_b32_e32 v43, 0xffff0000, v14
	v_lshlrev_b32_e32 v14, 16, v15
	v_and_b32_e32 v15, 0xffff0000, v15
	v_pk_mul_f32 v[44:45], v[54:55], v[44:45] op_sel_hi:[0,1]
	v_pk_mul_f32 v[8:9], v[54:55], v[8:9] op_sel_hi:[0,1]
	v_pk_mul_f32 v[10:11], v[54:55], v[10:11] op_sel_hi:[0,1]
	v_add_f32_e32 v39, v56, v39
	v_lshlrev_b32_e32 v50, 16, v6
	v_and_b32_e32 v51, 0xffff0000, v6
	v_lshlrev_b32_e32 v6, 16, v7
	v_and_b32_e32 v7, 0xffff0000, v7
	v_pk_fma_f32 v[8:9], v[52:53], v[12:13], v[8:9] op_sel_hi:[0,1,1]
	v_pk_fma_f32 v[12:13], v[52:53], v[40:41], v[44:45] op_sel_hi:[0,1,1]
	v_pk_fma_f32 v[10:11], v[52:53], v[14:15], v[10:11] op_sel_hi:[0,1,1]
	v_div_scale_f32 v40, s[4:5], v39, v39, 1.0
	v_pk_fma_f32 v[6:7], v[56:57], v[6:7], v[10:11] op_sel_hi:[0,1,1]
	v_rcp_f32_e32 v10, v40
	v_pk_mul_f32 v[46:47], v[54:55], v[46:47] op_sel_hi:[0,1]
	v_div_scale_f32 v41, vcc, 1.0, v39, 1.0
	v_fma_f32 v11, -v40, v10, 1.0
	v_fmac_f32_e32 v10, v11, v10
	v_lshlrev_b32_e32 v48, 16, v4
	v_and_b32_e32 v49, 0xffff0000, v4
	v_lshlrev_b32_e32 v4, 16, v5
	v_and_b32_e32 v5, 0xffff0000, v5
	v_pk_fma_f32 v[14:15], v[52:53], v[42:43], v[46:47] op_sel_hi:[0,1,1]
	v_mul_f32_e32 v11, v41, v10
	v_pk_fma_f32 v[4:5], v[56:57], v[4:5], v[8:9] op_sel_hi:[0,1,1]
	v_pk_fma_f32 v[8:9], v[56:57], v[50:51], v[14:15] op_sel_hi:[0,1,1]
	v_fma_f32 v14, -v40, v11, v41
	v_fmac_f32_e32 v11, v14, v10
	v_fma_f32 v14, -v40, v11, v41
	v_div_fmas_f32 v10, v14, v10, v11
	v_pk_fma_f32 v[12:13], v[56:57], v[48:49], v[12:13] op_sel_hi:[0,1,1]
	v_div_fixup_f32 v10, v10, v39, 1.0
	v_pk_mul_f32 v[14:15], v[10:11], v[4:5] op_sel_hi:[0,1]
	v_pk_mul_f32 v[4:5], v[10:11], v[12:13] op_sel_hi:[0,1]
	v_pk_mul_f32 v[12:13], v[10:11], v[6:7] op_sel_hi:[0,1]
	v_pk_mul_f32 v[6:7], v[10:11], v[8:9] op_sel_hi:[0,1]
	v_cvt_pk_bf16_f32 v4, v4, v5
	v_cvt_pk_bf16_f32 v5, v14, v15
	v_cvt_pk_bf16_f32 v6, v6, v7
	v_cvt_pk_bf16_f32 v7, v12, v13
	global_store_dwordx4 v[34:35], v[4:7], off offset:1024
	s_cbranch_scc0 .LBB0_396
